# v16 + moba_bucket item decode reads gcnt from LDS (kept at phase start) instead of dependent global load, decode vmcnt(0) dropped
# speedup vs baseline: 1.0456x; 1.0016x over previous
.LBB0_1448:
	s_or_b64 exec, exec, s[0:1]
	v_readlane_b32 s0, v237, 56
	v_readlane_b32 s1, v237, 57
	s_add_u32 s0, s0, 0x3d00100
	s_waitcnt lgkmcnt(0)
	v_mov_b32_e32 v0, v128
	s_barrier
	s_addc_u32 s1, s1, 0
	v_readlane_b32 s2, v237, 58
	v_ashrrev_i32_e32 v1, 31, v0
	v_lshl_add_u64 v[2:3], v[0:1], 2, s[0:1]
	global_load_dword v2, v[2:3], off
	v_mov_b32_e32 v1, 0x12c00
	v_lshl_add_u32 v1, v0, 2, v1
	s_barrier
	v_readlane_b32 s3, v237, 59
	v_cmp_lt_i32_e32 vcc, 0, v0
	s_waitcnt vmcnt(0)
	ds_write_b32 v1, v2 offset:1024
	v_add_u32_e32 v2, 63, v2
	v_ashrrev_i32_e32 v2, 6, v2
	ds_write_b32 v1, v2
	s_waitcnt lgkmcnt(0)
	s_barrier
	ds_read_b32 v2, v1
	s_and_saveexec_b64 s[2:3], vcc
	s_cbranch_execz .LBB0_1450
	v_add_u32_e32 v3, -4, v1
	ds_read_b32 v3, v3
	s_waitcnt lgkmcnt(0)
	v_add_u32_e32 v2, v3, v2

.LBB0_1472:
	s_add_i32 s12, s11, s10
	s_ashr_i32 s12, s12, 1
	s_lshl_b32 s13, s12, 2
	s_add_i32 s13, s13, 0x12c00
	v_mov_b32_e32 v0, s13
	ds_read_b32 v0, v0
	s_add_i32 s13, s12, 1
	s_waitcnt lgkmcnt(0)
	v_readfirstlane_b32 s15, v0
	s_cmp_gt_i32 s15, s21
	s_cselect_b32 s11, s12, s11
	s_cselect_b32 s10, s10, s13
	s_cmp_lt_i32 s10, s11
	s_cbranch_scc1 .LBB0_1472
	s_lshl_b32 s11, s10, 2
	s_ashr_i32 s12, s10, 6
	s_add_i32 s11, s11, 0x12c00
	s_mul_hi_i32 s13, s12, 0x7e0000
	s_mul_i32 s12, s12, 0x7e0000
	v_mov_b32_e32 v0, s11
	s_add_u32 s11, s4, s12
	s_addc_u32 s15, s5, s13
	s_and_b32 s12, s10, 63
	ds_read_b32 v52, v0 offset:1024
	ds_read_b32 v0, v0
	s_add_i32 s22, s12, -1
	s_mul_i32 s13, s12, 63
	s_mul_i32 s12, s22, s12
	s_lshr_b32 s22, s12, 31
	s_add_i32 s12, s12, s22
	s_sext_i32_i16 s12, s12
	s_waitcnt lgkmcnt(0)
	v_sub_u32_e32 v0, s21, v0
	s_lshr_b32 s12, s12, 1
	v_lshlrev_b32_e32 v0, 6, v0
	s_sub_i32 s12, 0, s12
	s_sext_i32_i16 s12, s12
	s_add_i32 s13, s13, s12
	s_lshl_b32 s12, s13, 10
	s_ashr_i32 s13, s12, 31
	s_lshl_b64 s[12:13], s[12:13], 2
	s_add_u32 s12, s11, s12
	s_addc_u32 s13, s15, s13
	v_add_u32_e32 v0, v52, v0
	v_add_u32_e32 v0, 63, v0
	v_and_b32_e32 v54, 0xffffffc0, v0
	v_add_u32_e32 v0, v54, v47
	v_cmp_lt_i32_e32 vcc, v0, v52
	s_nop 1
	v_cndmask_b32_e32 v0, 0, v0, vcc
	v_ashrrev_i32_e32 v1, 31, v0
	v_lshl_add_u64 v[0:1], v[0:1], 2, s[12:13]
	global_load_dword v56, v[0:1], off
